# diff2: uniform-bias LDS reads issued at the end of the previous MFMA segment, slow-path address math moved off the fast path (on top of v25)
# speedup vs baseline: 1.0216x; 1.0216x over previous
; #define LAS __attribute__((address_space(3)))
; #define D2_LOADK(tt) do { const unsigned char* zt_ = Zt + (size_t)(tt) * (64 * 1024 * 2); gk0 = *(const v4u*)(zt_ + oK); gk1 = *(const v4u*)(zt_ + oK + 1024); } while (0)
; #define D2_LOADV(tt) do { const unsigned char* zt_ = ZtV + (size_t)(tt) * (64 * 1024 * 2); gv0 = *(const v4u*)(zt_ + oV); gv1 = *(const v4u*)(zt_ + oV + 32 * 1024 * 2); } while (0)
; __device__ __forceinline__ void diff2_item(const Params& p, LAS unsigned char* lds, const int item, const float lam, const float lam_init) {
;     ...
;     v16f O[4]; float m_ = NEGBIG, l_ = 0.f;
; #pragma unroll
;     for (int eb = 0; eb < 4; ++eb)
; #pragma unroll
;         for (int i = 0; i < 16; ++i) O[eb][i] = 0.f;
;     const int rowK = tid >> 3, cc = tid & 7, rowV = tid >> 4, ccV = tid & 15;
;     const unsigned char* Zt = (const unsigned char*)(Z + (size_t)T * OFF_DK + ((size_t)b * 2048) * 1024 + hh * 64);
;     const unsigned char* ZtV = (const unsigned char*)(Z + (size_t)T * OFF_DV + ((size_t)b * 2048) * 1024 + hh * 128);
;     const unsigned oK = (unsigned)(rowK * 1024 + cc * 8) * 2u;
;     const unsigned oV = (unsigned)(rowV * 1024 + ccV * 8) * 2u;
;     LAS unsigned char* dK = lds + rowK * 144 + cc * 16;
;     LAS unsigned char* dV = lds + D2_VR + rowV * 320 + ccV * 16;
;     ...
;     v4u gk0, gk1, gv0, gv1;
;     D2_LOADK(0);
;     *(LAS v4u*)dK = gk0; *(LAS v4u*)(dK + D2_K1) = gk1;
;     D2_LOADK(1); D2_LOADV(0);
;     __syncthreads();
;     const float c1 = 0.125f * LOG2E;
;     const LAS unsigned char* kb0 = lds + mp * D2_K1 + r * 144 + h * 16;
;     const int q_ = (lane >> 2) & 3, p_ = lane & 3, g1_ = (lane >> 4) & 1;
;     const LAS unsigned char* vb_lane = lds + D2_VR + ((4 * h + q_) * 320 + (16 * g1_ + 4 * p_) * 2);
;     const int rel0 = 4 * h - (q0w + r);
;     v16f S0, S1; v8s P0[2], P1[2];
.LBB0_325:
	s_or_b64 exec, exec, s[10:11]
	s_movk_i32 s10, 0x140
	v_mul_lo_u32 v6, v7, s10
	v_readlane_b32 s10, v248, 33
	s_add_u32 s10, s10, s6
	v_readlane_b32 s11, v248, 34
	s_addc_u32 s11, s11, s7
	v_and_b32_e32 v177, 63, v2
	v_lshlrev_b32_e32 v176, 3, v8
	v_add3_u32 v182, 0, v6, v148
	v_lshrrev_b32_e32 v6, 2, v2
	v_lshlrev_b32_e32 v7, 2, v8
	v_and_b32_e32 v8, 16, v2
	v_lshlrev_b32_e32 v2, 2, v2
	v_lshl_add_u64 v[150:151], s[10:11], 0, v[0:1]
	s_mov_b64 s[98:99], 0x1aa40000
	v_lshl_add_u64 v[150:151], v[150:151], 0, s[98:99]
	v_readlane_b32 s10, v248, 35
	v_and_or_b32 v6, v6, 3, v7
	v_and_or_b32 v2, v2, 12, v8
	s_add_u32 s6, s10, s6
	v_readlane_b32 s10, v248, 36
	v_mul_u32_u24_e32 v6, 0x140, v6
	v_lshlrev_b32_e32 v2, 1, v2
	v_add3_u32 v0, s52, v3, v174
	s_addc_u32 s7, s10, s7
	v_mov_b32_e32 v14, v1
	v_mov_b32_e32 v15, v1
	v_add3_u32 v180, 0, v6, v2
	v_sub_u32_e32 v183, v7, v0
	v_lshl_add_u64 v[152:153], s[6:7], 0, v[4:5]
	s_mov_b64 s[98:99], 0x1ca20000
	v_lshl_add_u64 v[152:153], v[152:153], 0, s[98:99]
	v_mov_b32_e32 v0, v1
	v_mov_b32_e32 v2, v1
	v_mov_b32_e32 v3, v1
	v_mov_b32_e32 v4, v1
	v_mov_b32_e32 v5, v1
	v_mov_b32_e32 v6, v1
	v_mov_b32_e32 v7, v1
	v_mov_b32_e32 v8, v1
	v_mov_b32_e32 v9, v1
	v_mov_b32_e32 v10, v1
	v_mov_b32_e32 v11, v1
	v_mov_b32_e32 v12, v1
	v_mov_b32_e32 v13, v1
	v_mov_b64_e32 v[64:65], v[14:15]
	v_mov_b64_e32 v[48:49], v[14:15]
	v_mov_b64_e32 v[32:33], v[14:15]
	v_mov_b64_e32 v[62:63], v[12:13]
	v_mov_b64_e32 v[60:61], v[10:11]
	v_mov_b64_e32 v[58:59], v[8:9]
	v_mov_b64_e32 v[56:57], v[6:7]
	v_mov_b64_e32 v[54:55], v[4:5]
	v_mov_b64_e32 v[52:53], v[2:3]
	v_mov_b64_e32 v[50:51], v[0:1]
	v_mov_b64_e32 v[46:47], v[12:13]
	v_mov_b64_e32 v[44:45], v[10:11]
	v_mov_b64_e32 v[42:43], v[8:9]
	v_mov_b64_e32 v[40:41], v[6:7]
	v_mov_b64_e32 v[38:39], v[4:5]
	v_mov_b64_e32 v[36:37], v[2:3]
	v_mov_b64_e32 v[34:35], v[0:1]
	v_mov_b64_e32 v[30:31], v[12:13]
	v_mov_b64_e32 v[28:29], v[10:11]
	v_mov_b64_e32 v[26:27], v[8:9]
	v_mov_b64_e32 v[24:25], v[6:7]
	v_mov_b64_e32 v[22:23], v[4:5]
	v_mov_b64_e32 v[20:21], v[2:3]
	v_mov_b64_e32 v[18:19], v[0:1]
	v_mov_b64_e32 v[16:17], v[14:15]
	s_mov_b32 s19, 0
	v_mov_b32_e32 v184, 0xf149f2ca
	v_mov_b32_e32 v154, 0
	s_mov_b64 s[6:7], 0
	v_mov_b64_e32 v[14:15], v[12:13]
	v_mov_b64_e32 v[12:13], v[10:11]
	v_mov_b64_e32 v[10:11], v[8:9]
	v_mov_b64_e32 v[8:9], v[6:7]
	v_mov_b64_e32 v[6:7], v[4:5]
	v_mov_b64_e32 v[4:5], v[2:3]
	v_mov_b64_e32 v[2:3], v[0:1]
	s_barrier
	v_add_u32_e32 v253, 32, v183
	v_med3_i32 v252, v183, s16, v214
	v_med3_i32 v253, v253, s16, v214
	v_lshl_add_u32 v252, v252, 2, s23
	v_lshl_add_u32 v253, v253, 2, s23
	ds_read_b32 v254, v252 offset:2688
	ds_read_b32 v255, v253 offset:2688

; __device__ __forceinline__ void d2_qk(const LAS unsigned char* Kb, const v8s (&Q)[4], v16f& S) {
;     const v16f z = {0.f, 0.f, 0.f, 0.f, 0.f, 0.f, 0.f, 0.f, 0.f, 0.f, 0.f, 0.f, 0.f, 0.f, 0.f, 0.f};
;     const v8s k0 = *(const LAS v8s*)Kb, k1 = *(const LAS v8s*)(Kb + 32), k2 = *(const LAS v8s*)(Kb + 64), k3 = *(const LAS v8s*)(Kb + 96);
;     __builtin_amdgcn_sched_barrier(0);
;     S = MFMA32(k0, Q[0], z); S = MFMA32(k1, Q[1], S); S = MFMA32(k2, Q[2], S); S = MFMA32(k3, Q[3], S);
;     __builtin_amdgcn_sched_barrier(0);
; }
; __device__ __forceinline__ void d2_softmax(v16f& S, const float c1, const LAS float* tp, float& m, float& l, v16f (&O)[4], v8s (&P)[2]) {
;     float tmax = NEGBIG;
; #pragma unroll
;     for (int i = 0; i < 16; ++i) { S[i] = S[i] * c1 + tp[(i & 3) + 8 * (i >> 2)]; tmax = fmaxf(tmax, S[i]); }
;     tmax = fmaxf(tmax, __shfl_xor(tmax, 32));
;     const float mo = m;
;     if (__any(tmax > mo + 8.f)) {
;         const float mn = (tmax > mo + 8.f) ? tmax : mo;
;         const float alpha = __builtin_amdgcn_exp2f(mo - mn);
;         l *= alpha;
; #pragma unroll
;         for (int eb = 0; eb < 4; ++eb)
; #pragma unroll
;             for (int i = 0; i < 16; ++i) O[eb][i] *= alpha;
;         m = mn;
;     }
;     const float mc = m;
;     float ps = 0.f;
; #pragma unroll
;     for (int i = 0; i < 16; ++i) { S[i] = __builtin_amdgcn_exp2f(S[i] - mc); ps += S[i]; }
;     l += ps;
; #pragma unroll
;     for (int s2 = 0; s2 < 2; ++s2) { v4u w; w.x = pk2(S[8 * s2 + 0], S[8 * s2 + 1]); w.y = pk2(S[8 * s2 + 2], S[8 * s2 + 3]); w.z = pk2(S[8 * s2 + 4], S[8 * s2 + 5]); w.w = pk2(S[8 * s2 + 6], S[8 * s2 + 7]);
;         P[s2] = __builtin_bit_cast(v8s, w); }
; }
; __device__ __forceinline__ void d2_pv(const LAS unsigned char* vb0, const v8s (&P)[2], v16f (&O)[4]) {
;     const LAS unsigned char* va = vb0; const LAS unsigned char* vc = vb0 + 16 * 320;
;     const v4s l0 = TRR(va), h0 = TRR(va + 2560), l1 = TRR(va + 64), h1 = TRR(va + 2624), l2 = TRR(va + 128), h2 = TRR(va + 2688), l3 = TRR(va + 192), h3 = TRR(va + 2752);
;     __builtin_amdgcn_sched_barrier(0);
;     const v4s m0 = TRR(vc), n0 = TRR(vc + 2560), m1 = TRR(vc + 64), n1 = TRR(vc + 2624), m2 = TRR(vc + 128), n2 = TRR(vc + 2688), m3 = TRR(vc + 192), n3 = TRR(vc + 2752);
;     O[0] = MFMA32(__builtin_shufflevector(l0, h0, 0, 1, 2, 3, 4, 5, 6, 7), P[0], O[0]);
.LBB0_333:
	s_mul_i32 s19, s18, 0x4800
	v_add_u32_e32 v0, s19, v181
	ds_read_b128 v[66:69], v0
	ds_read_b128 v[82:85], v0 offset:32
	ds_read_b128 v[86:89], v0 offset:64
	ds_read_b128 v[90:93], v0 offset:96
	s_waitcnt lgkmcnt(3)
	v_mfma_f32_32x32x16_bf16 v[66:81], v[66:69], v[98:101], 0
	s_waitcnt lgkmcnt(2)
	v_mfma_f32_32x32x16_bf16 v[66:81], v[82:85], v[102:105], v[66:81]
	s_waitcnt lgkmcnt(1)
	v_mfma_f32_32x32x16_bf16 v[66:81], v[86:89], v[106:109], v[66:81]
	s_waitcnt lgkmcnt(0)
	v_mfma_f32_32x32x16_bf16 v[66:81], v[90:93], v[110:113], v[66:81]
	ds_read_b128 v[82:85], v0 offset:4608
	ds_read_b128 v[156:159], v0 offset:4640
	ds_read_b128 v[186:189], v0 offset:4672
	ds_read_b128 v[190:193], v0 offset:4704
	s_waitcnt lgkmcnt(3)
	v_mfma_f32_32x32x16_bf16 v[82:97], v[82:85], v[98:101], 0
	s_waitcnt lgkmcnt(2)
	v_mfma_f32_32x32x16_bf16 v[82:97], v[156:159], v[102:105], v[82:97]
	s_waitcnt lgkmcnt(1)
	v_mfma_f32_32x32x16_bf16 v[82:97], v[186:189], v[106:109], v[82:97]
	s_waitcnt lgkmcnt(0)
	v_mfma_f32_32x32x16_bf16 v[82:97], v[190:193], v[110:113], v[82:97]
	s_cmp_eq_u32 s6, 0
	s_cbranch_scc1 .LBB0_335
	s_xor_b32 s18, s18, 1
	s_mulk_i32 s18, 0x5000
	v_add_u32_e32 v0, s18, v180
	ds_read_b64_tr_b16 v[156:157], v0 offset:36864
	ds_read_b64_tr_b16 v[186:187], v0 offset:36928
	ds_read_b64_tr_b16 v[190:191], v0 offset:36992
	ds_read_b64_tr_b16 v[194:195], v0 offset:37056
	ds_read_b64_tr_b16 v[158:159], v0 offset:39424
	ds_read_b64_tr_b16 v[188:189], v0 offset:39488
	ds_read_b64_tr_b16 v[192:193], v0 offset:39552
	ds_read_b64_tr_b16 v[196:197], v0 offset:39616
	s_waitcnt lgkmcnt(3)
	v_mfma_f32_32x32x16_bf16 v[50:65], v[156:159], v[134:137], v[50:65]
	s_waitcnt lgkmcnt(2)
	v_mfma_f32_32x32x16_bf16 v[34:49], v[186:189], v[134:137], v[34:49]
	s_waitcnt lgkmcnt(1)
	v_mfma_f32_32x32x16_bf16 v[18:33], v[190:193], v[134:137], v[18:33]
	ds_read_b64_tr_b16 v[156:157], v0 offset:41984
	ds_read_b64_tr_b16 v[186:187], v0 offset:42048
	ds_read_b64_tr_b16 v[190:191], v0 offset:42112
	ds_read_b64_tr_b16 v[198:199], v0 offset:42176
	ds_read_b64_tr_b16 v[158:159], v0 offset:44544
	ds_read_b64_tr_b16 v[188:189], v0 offset:44608
	ds_read_b64_tr_b16 v[192:193], v0 offset:44672
	ds_read_b64_tr_b16 v[200:201], v0 offset:44736
	s_waitcnt lgkmcnt(8)
	v_mfma_f32_32x32x16_bf16 v[2:17], v[194:197], v[134:137], v[2:17]
	s_waitcnt lgkmcnt(3)
	v_mfma_f32_32x32x16_bf16 v[50:65], v[156:159], v[130:133], v[50:65]
	s_waitcnt lgkmcnt(2)
	v_mfma_f32_32x32x16_bf16 v[34:49], v[186:189], v[130:133], v[34:49]
	s_waitcnt lgkmcnt(1)
	v_mfma_f32_32x32x16_bf16 v[18:33], v[190:193], v[130:133], v[18:33]
	s_waitcnt lgkmcnt(0)
	v_mfma_f32_32x32x16_bf16 v[2:17], v[198:201], v[130:133], v[2:17]
	ds_read_b64_tr_b16 v[156:157], v0 offset:47104
	ds_read_b64_tr_b16 v[186:187], v0 offset:47168
	ds_read_b64_tr_b16 v[190:191], v0 offset:47232
	ds_read_b64_tr_b16 v[194:195], v0 offset:47296
	ds_read_b64_tr_b16 v[158:159], v0 offset:49664
	ds_read_b64_tr_b16 v[188:189], v0 offset:49728
	ds_read_b64_tr_b16 v[192:193], v0 offset:49792
	ds_read_b64_tr_b16 v[196:197], v0 offset:49856
	s_waitcnt lgkmcnt(3)
	v_mfma_f32_32x32x16_bf16 v[50:65], v[156:159], v[142:145], v[50:65]
	s_waitcnt lgkmcnt(2)
	v_mfma_f32_32x32x16_bf16 v[34:49], v[186:189], v[142:145], v[34:49]
	s_waitcnt lgkmcnt(1)
	v_mfma_f32_32x32x16_bf16 v[18:33], v[190:193], v[142:145], v[18:33]
	ds_read_b64_tr_b16 v[156:157], v0 offset:52224
	ds_read_b64_tr_b16 v[186:187], v0 offset:52288
	ds_read_b64_tr_b16 v[190:191], v0 offset:52352
	ds_read_b64_tr_b16 v[198:199], v0 offset:52416
	ds_read_b64_tr_b16 v[158:159], v0 offset:54784
	ds_read_b64_tr_b16 v[188:189], v0 offset:54848
	ds_read_b64_tr_b16 v[192:193], v0 offset:54912
	ds_read_b64_tr_b16 v[200:201], v0 offset:54976
	s_waitcnt lgkmcnt(8)
	v_mfma_f32_32x32x16_bf16 v[2:17], v[194:197], v[142:145], v[2:17]
	s_waitcnt lgkmcnt(3)
	v_mfma_f32_32x32x16_bf16 v[50:65], v[156:159], v[138:141], v[50:65]
	s_waitcnt lgkmcnt(2)
	v_mfma_f32_32x32x16_bf16 v[34:49], v[186:189], v[138:141], v[34:49]
	s_waitcnt lgkmcnt(1)
	v_mfma_f32_32x32x16_bf16 v[18:33], v[190:193], v[138:141], v[18:33]
	s_waitcnt lgkmcnt(0)
	v_mfma_f32_32x32x16_bf16 v[2:17], v[198:201], v[138:141], v[2:17]
	v_add_u32_e32 v253, 32, v183
	v_med3_i32 v252, v183, s16, v214
	v_med3_i32 v253, v253, s16, v214
	v_lshl_add_u32 v252, v252, 2, s23
	v_lshl_add_u32 v253, v253, 2, s23
	ds_read_b32 v254, v252 offset:2688
	ds_read_b32 v255, v253 offset:2688
; #define LAS __attribute__((address_space(3)))
; __device__ __forceinline__ void d2_softmax(v16f& S, const float c1, const LAS float* tp, float& m, float& l, v16f (&O)[4], v8s (&P)[2]) {
;     float tmax = NEGBIG;
; #pragma unroll
;     for (int i = 0; i < 16; ++i) { S[i] = S[i] * c1 + tp[(i & 3) + 8 * (i >> 2)]; tmax = fmaxf(tmax, S[i]); }
;     tmax = fmaxf(tmax, __shfl_xor(tmax, 32));
;     const float mo = m;
;     if (__any(tmax > mo + 8.f)) {
;         const float mn = (tmax > mo + 8.f) ? tmax : mo;
;         const float alpha = __builtin_amdgcn_exp2f(mo - mn);
;         l *= alpha;
; #pragma unroll
;         for (int eb = 0; eb < 4; ++eb)
; #pragma unroll
;             for (int i = 0; i < 16; ++i) O[eb][i] *= alpha;
;         m = mn;
.LBB0_335:
	s_andn2_saveexec_b64 s[18:19], s[10:11]
	s_cbranch_execz .LBB0_341
	s_setprio 3
	v_readfirstlane_b32 s98, v183
	s_mov_b32 s100, 0xfff9f990
	s_mov_b32 s101, -1
	s_add_i32 s99, s98, 32
	s_abs_i32 s98, s98
	s_abs_i32 s99, s99
	s_lshr_b32 s98, s98, 5
	s_lshr_b32 s99, s99, 5
	s_bitcmp1_b64 s[100:101], s99
	s_cbranch_scc1 .Ld2x0_i1f
	v_add_u32_e32 v156, 32, v183
	v_med3_i32 v156, v156, s16, v214
	v_lshl_add_u32 v156, v156, 2, s23
	v_add_u32_e32 v156, 0xa80, v156
	ds_read2_b32 v[186:187], v156 offset1:1
	ds_read2_b32 v[188:189], v156 offset0:2 offset1:3
	ds_read2_b32 v[190:191], v156 offset0:8 offset1:9
	ds_read2_b32 v[192:193], v156 offset0:10 offset1:11
	ds_read2_b32 v[194:195], v156 offset0:16 offset1:17
	ds_read2_b32 v[196:197], v156 offset0:18 offset1:19
	ds_read2_b32 v[198:199], v156 offset0:24 offset1:25
	ds_read2_b32 v[200:201], v156 offset0:26 offset1:27
.Ld2x0_i1f:
.Ld2x0_i1d:
	s_bitcmp1_b64 s[100:101], s98
	s_cbranch_scc1 .Ld2x0_c0f
	v_med3_i32 v0, v183, s16, v214
	v_lshl_add_u32 v0, v0, 2, s23
	v_add_u32_e32 v0, 0xa80, v0
	ds_read2_b32 v[134:135], v0 offset1:1
	ds_read2_b32 v[130:131], v0 offset0:2 offset1:3
	ds_read2_b32 v[132:133], v0 offset0:8 offset1:9
	ds_read2_b32 v[136:137], v0 offset0:10 offset1:11
	ds_read2_b32 v[138:139], v0 offset0:16 offset1:17
	ds_read2_b32 v[140:141], v0 offset0:18 offset1:19
	ds_read2_b32 v[142:143], v0 offset0:24 offset1:25
	s_waitcnt lgkmcnt(6)
	ds_read2_b32 v[144:145], v0 offset0:26 offset1:27
	v_fmac_f32_e32 v135, 0x3e38aa3b, v67
	v_fmamk_f32 v0, v66, 0x3e38aa3b, v134
	v_max3_f32 v66, v0, s15, v135
	s_waitcnt lgkmcnt(6)
	v_fmamk_f32 v68, v68, 0x3e38aa3b, v130
	v_fmac_f32_e32 v131, 0x3e38aa3b, v69
	v_max3_f32 v66, v66, v68, v131
	s_waitcnt lgkmcnt(5)
	v_fmamk_f32 v70, v70, 0x3e38aa3b, v132
	v_fmac_f32_e32 v133, 0x3e38aa3b, v71
	v_max3_f32 v66, v66, v70, v133
	s_waitcnt lgkmcnt(4)
	v_fmamk_f32 v72, v72, 0x3e38aa3b, v136
	v_fmac_f32_e32 v137, 0x3e38aa3b, v73
	v_max3_f32 v66, v66, v72, v137
	s_waitcnt lgkmcnt(3)
	v_fmamk_f32 v74, v74, 0x3e38aa3b, v138
	v_fmac_f32_e32 v139, 0x3e38aa3b, v75
	v_max3_f32 v66, v66, v74, v139
	s_waitcnt lgkmcnt(2)
	v_fmamk_f32 v76, v76, 0x3e38aa3b, v140
	v_fmac_f32_e32 v141, 0x3e38aa3b, v77
	v_max3_f32 v66, v66, v76, v141
	s_waitcnt lgkmcnt(1)
	v_fmamk_f32 v78, v78, 0x3e38aa3b, v142
	v_fmac_f32_e32 v143, 0x3e38aa3b, v79
	v_max3_f32 v66, v66, v78, v143
	s_waitcnt lgkmcnt(0)
	v_fmamk_f32 v80, v80, 0x3e38aa3b, v144
	v_fmac_f32_e32 v145, 0x3e38aa3b, v81
	v_max3_f32 v66, v66, v80, v145
	v_add_f32_e32 v130, 0x41000000, v184
	v_cmp_gt_f32_e32 vcc, v66, v130
	s_cbranch_vccz .Ld2x0_a
	v_mov_b32_e32 v67, v66
	s_nop 1
	v_permlane32_swap_b32_e32 v67, v66
	v_max_f32_e32 v66, v66, v67
	v_cmp_gt_f32_e32 vcc, v66, v130
	s_nop 1
	v_cndmask_b32_e32 v67, v184, v66, vcc
	v_sub_f32_e32 v66, v184, v67
	v_exp_f32_e32 v66, v66
	v_add_f32_e32 v130, 0x41000000, v67
	v_mov_b32_e32 v184, v67
	v_mul_f32_e32 v154, v154, v66
	v_pk_mul_f32 v[64:65], v[64:65], v[66:67] op_sel_hi:[1,0]
	v_pk_mul_f32 v[62:63], v[62:63], v[66:67] op_sel_hi:[1,0]
	v_pk_mul_f32 v[60:61], v[60:61], v[66:67] op_sel_hi:[1,0]
	v_pk_mul_f32 v[58:59], v[58:59], v[66:67] op_sel_hi:[1,0]
	v_pk_mul_f32 v[56:57], v[56:57], v[66:67] op_sel_hi:[1,0]
	v_pk_mul_f32 v[54:55], v[54:55], v[66:67] op_sel_hi:[1,0]
	v_pk_mul_f32 v[52:53], v[52:53], v[66:67] op_sel_hi:[1,0]
	v_pk_mul_f32 v[50:51], v[50:51], v[66:67] op_sel_hi:[1,0]
	v_pk_mul_f32 v[48:49], v[48:49], v[66:67] op_sel_hi:[1,0]
	v_pk_mul_f32 v[46:47], v[46:47], v[66:67] op_sel_hi:[1,0]
	v_pk_mul_f32 v[44:45], v[44:45], v[66:67] op_sel_hi:[1,0]
	v_pk_mul_f32 v[42:43], v[42:43], v[66:67] op_sel_hi:[1,0]
	v_pk_mul_f32 v[40:41], v[40:41], v[66:67] op_sel_hi:[1,0]
	v_pk_mul_f32 v[38:39], v[38:39], v[66:67] op_sel_hi:[1,0]
	v_pk_mul_f32 v[36:37], v[36:37], v[66:67] op_sel_hi:[1,0]
	v_pk_mul_f32 v[34:35], v[34:35], v[66:67] op_sel_hi:[1,0]
	v_pk_mul_f32 v[32:33], v[32:33], v[66:67] op_sel_hi:[1,0]
	v_pk_mul_f32 v[30:31], v[30:31], v[66:67] op_sel_hi:[1,0]
	v_pk_mul_f32 v[28:29], v[28:29], v[66:67] op_sel_hi:[1,0]
	v_pk_mul_f32 v[26:27], v[26:27], v[66:67] op_sel_hi:[1,0]
	v_pk_mul_f32 v[24:25], v[24:25], v[66:67] op_sel_hi:[1,0]
	v_pk_mul_f32 v[22:23], v[22:23], v[66:67] op_sel_hi:[1,0]
	v_pk_mul_f32 v[20:21], v[20:21], v[66:67] op_sel_hi:[1,0]
	v_pk_mul_f32 v[18:19], v[18:19], v[66:67] op_sel_hi:[1,0]
	v_pk_mul_f32 v[16:17], v[16:17], v[66:67] op_sel_hi:[1,0]
	v_pk_mul_f32 v[14:15], v[14:15], v[66:67] op_sel_hi:[1,0]
	v_pk_mul_f32 v[12:13], v[12:13], v[66:67] op_sel_hi:[1,0]
	v_pk_mul_f32 v[10:11], v[10:11], v[66:67] op_sel_hi:[1,0]
	v_pk_mul_f32 v[8:9], v[8:9], v[66:67] op_sel_hi:[1,0]
	v_pk_mul_f32 v[6:7], v[6:7], v[66:67] op_sel_hi:[1,0]
	v_pk_mul_f32 v[4:5], v[4:5], v[66:67] op_sel_hi:[1,0]
	v_pk_mul_f32 v[2:3], v[2:3], v[66:67] op_sel_hi:[1,0]

; #define LAS __attribute__((address_space(3)))
; __device__ __forceinline__ void d2_softmax(v16f& S, const float c1, const LAS float* tp, float& m, float& l, v16f (&O)[4], v8s (&P)[2]) {
;     float tmax = NEGBIG;
; #pragma unroll
;     for (int i = 0; i < 16; ++i) { S[i] = S[i] * c1 + tp[(i & 3) + 8 * (i >> 2)]; tmax = fmaxf(tmax, S[i]); }
;     tmax = fmaxf(tmax, __shfl_xor(tmax, 32));
;     const float mo = m;
;     if (__any(tmax > mo + 8.f)) {
;         const float mn = (tmax > mo + 8.f) ? tmax : mo;
;         const float alpha = __builtin_amdgcn_exp2f(mo - mn);
;         l *= alpha;
; #pragma unroll
;         for (int eb = 0; eb < 4; ++eb)
; #pragma unroll
;             for (int i = 0; i < 16; ++i) O[eb][i] *= alpha;
;         m = mn;
;     }
;     const float mc = m;
;     float ps = 0.f;
; #pragma unroll
;     for (int i = 0; i < 16; ++i) { S[i] = __builtin_amdgcn_exp2f(S[i] - mc); ps += S[i]; }
;     l += ps;
.Ld2x0_c0f:
	v_max3_f32 v135, v66, v67, v68
	v_max3_f32 v135, v135, v69, v70
	v_max3_f32 v135, v135, v71, v72
	v_max3_f32 v135, v135, v73, v74
	v_max3_f32 v135, v135, v75, v76
	v_max3_f32 v135, v135, v77, v78
	v_max3_f32 v135, v135, v79, v80
	v_max_f32_e32 v135, v135, v81
	v_add_f32_e32 v130, 0x41000000, v184
	s_waitcnt lgkmcnt(0)
	v_fmamk_f32 v135, v135, 0x3e38aa3b, v254
	v_cmp_gt_f32_e32 vcc, v135, v130
	s_cbranch_vccz .Ld2x0_f0a
	v_mov_b32_e32 v136, v135
	s_nop 1
	v_permlane32_swap_b32_e32 v136, v135
	v_max_f32_e32 v135, v135, v136
	v_cmp_gt_f32_e32 vcc, v135, v130
	s_nop 1
	v_cndmask_b32_e32 v137, v184, v135, vcc
	v_sub_f32_e32 v136, v184, v137
	v_exp_f32_e32 v136, v136
	v_add_f32_e32 v130, 0x41000000, v137
	v_mov_b32_e32 v184, v137
	v_mul_f32_e32 v154, v154, v136
	v_pk_mul_f32 v[64:65], v[64:65], v[136:137] op_sel_hi:[1,0]
	v_pk_mul_f32 v[62:63], v[62:63], v[136:137] op_sel_hi:[1,0]
	v_pk_mul_f32 v[60:61], v[60:61], v[136:137] op_sel_hi:[1,0]
	v_pk_mul_f32 v[58:59], v[58:59], v[136:137] op_sel_hi:[1,0]
	v_pk_mul_f32 v[56:57], v[56:57], v[136:137] op_sel_hi:[1,0]
	v_pk_mul_f32 v[54:55], v[54:55], v[136:137] op_sel_hi:[1,0]
	v_pk_mul_f32 v[52:53], v[52:53], v[136:137] op_sel_hi:[1,0]
	v_pk_mul_f32 v[50:51], v[50:51], v[136:137] op_sel_hi:[1,0]
	v_pk_mul_f32 v[48:49], v[48:49], v[136:137] op_sel_hi:[1,0]
	v_pk_mul_f32 v[46:47], v[46:47], v[136:137] op_sel_hi:[1,0]
	v_pk_mul_f32 v[44:45], v[44:45], v[136:137] op_sel_hi:[1,0]
	v_pk_mul_f32 v[42:43], v[42:43], v[136:137] op_sel_hi:[1,0]
	v_pk_mul_f32 v[40:41], v[40:41], v[136:137] op_sel_hi:[1,0]
	v_pk_mul_f32 v[38:39], v[38:39], v[136:137] op_sel_hi:[1,0]
	v_pk_mul_f32 v[36:37], v[36:37], v[136:137] op_sel_hi:[1,0]
	v_pk_mul_f32 v[34:35], v[34:35], v[136:137] op_sel_hi:[1,0]
	v_pk_mul_f32 v[32:33], v[32:33], v[136:137] op_sel_hi:[1,0]
	v_pk_mul_f32 v[30:31], v[30:31], v[136:137] op_sel_hi:[1,0]
	v_pk_mul_f32 v[28:29], v[28:29], v[136:137] op_sel_hi:[1,0]
	v_pk_mul_f32 v[26:27], v[26:27], v[136:137] op_sel_hi:[1,0]
	v_pk_mul_f32 v[24:25], v[24:25], v[136:137] op_sel_hi:[1,0]
	v_pk_mul_f32 v[22:23], v[22:23], v[136:137] op_sel_hi:[1,0]
	v_pk_mul_f32 v[20:21], v[20:21], v[136:137] op_sel_hi:[1,0]
	v_pk_mul_f32 v[18:19], v[18:19], v[136:137] op_sel_hi:[1,0]
	v_pk_mul_f32 v[16:17], v[16:17], v[136:137] op_sel_hi:[1,0]
	v_pk_mul_f32 v[14:15], v[14:15], v[136:137] op_sel_hi:[1,0]
	v_pk_mul_f32 v[12:13], v[12:13], v[136:137] op_sel_hi:[1,0]
	v_pk_mul_f32 v[10:11], v[10:11], v[136:137] op_sel_hi:[1,0]
	v_pk_mul_f32 v[8:9], v[8:9], v[136:137] op_sel_hi:[1,0]
	v_pk_mul_f32 v[6:7], v[6:7], v[136:137] op_sel_hi:[1,0]
	v_pk_mul_f32 v[4:5], v[4:5], v[136:137] op_sel_hi:[1,0]
	v_pk_mul_f32 v[2:3], v[2:3], v[136:137] op_sel_hi:[1,0]
.Ld2x0_f0a:
	v_sub_f32_e32 v134, v254, v184
	v_fmamk_f32 v66, v66, 0x3e38aa3b, v134
	v_exp_f32_e32 v66, v66
	v_fmamk_f32 v67, v67, 0x3e38aa3b, v134
	v_exp_f32_e32 v67, v67
	v_fmamk_f32 v68, v68, 0x3e38aa3b, v134
	v_exp_f32_e32 v68, v68
	v_fmamk_f32 v69, v69, 0x3e38aa3b, v134
	v_exp_f32_e32 v69, v69
	v_fmamk_f32 v70, v70, 0x3e38aa3b, v134
	v_exp_f32_e32 v70, v70
	v_fmamk_f32 v71, v71, 0x3e38aa3b, v134
	v_add_f32_e32 v0, v66, v67
	v_exp_f32_e32 v71, v71
	v_fmamk_f32 v72, v72, 0x3e38aa3b, v134
	v_add_f32_e32 v0, v68, v0
	v_exp_f32_e32 v72, v72
	v_fmamk_f32 v73, v73, 0x3e38aa3b, v134
	v_add_f32_e32 v0, v69, v0
	v_exp_f32_e32 v73, v73
	v_fmamk_f32 v74, v74, 0x3e38aa3b, v134
	v_add_f32_e32 v0, v70, v0
	v_exp_f32_e32 v74, v74
	v_fmamk_f32 v75, v75, 0x3e38aa3b, v134
	v_add_f32_e32 v0, v71, v0
	v_exp_f32_e32 v75, v75
	v_fmamk_f32 v76, v76, 0x3e38aa3b, v134
	v_add_f32_e32 v0, v72, v0
	v_exp_f32_e32 v76, v76
	v_fmamk_f32 v77, v77, 0x3e38aa3b, v134
	v_add_f32_e32 v0, v73, v0
	v_exp_f32_e32 v77, v77
	v_fmamk_f32 v78, v78, 0x3e38aa3b, v134
	v_add_f32_e32 v0, v74, v0
	v_exp_f32_e32 v78, v78
	v_fmamk_f32 v79, v79, 0x3e38aa3b, v134
	v_add_f32_e32 v0, v75, v0
	v_exp_f32_e32 v79, v79
	v_fmamk_f32 v80, v80, 0x3e38aa3b, v134
	v_add_f32_e32 v0, v76, v0
	v_exp_f32_e32 v80, v80
	v_fmamk_f32 v81, v81, 0x3e38aa3b, v134
	v_add_f32_e32 v0, v77, v0
	v_exp_f32_e32 v81, v81

; #define LAS __attribute__((address_space(3)))
; __device__ __forceinline__ void d2_softmax(v16f& S, const float c1, const LAS float* tp, float& m, float& l, v16f (&O)[4], v8s (&P)[2]) {
;     float tmax = NEGBIG;
; #pragma unroll
;     for (int i = 0; i < 16; ++i) { S[i] = S[i] * c1 + tp[(i & 3) + 8 * (i >> 2)]; tmax = fmaxf(tmax, S[i]); }
;     tmax = fmaxf(tmax, __shfl_xor(tmax, 32));
;     const float mo = m;
;     if (__any(tmax > mo + 8.f)) {
;         const float mn = (tmax > mo + 8.f) ? tmax : mo;
;         const float alpha = __builtin_amdgcn_exp2f(mo - mn);
;         l *= alpha;
; #pragma unroll
;         for (int eb = 0; eb < 4; ++eb)
; #pragma unroll
;             for (int i = 0; i < 16; ++i) O[eb][i] *= alpha;
;         m = mn;
;     }
;     const float mc = m;
;     float ps = 0.f;
; #pragma unroll
;     for (int i = 0; i < 16; ++i) { S[i] = __builtin_amdgcn_exp2f(S[i] - mc); ps += S[i]; }
;     l += ps;
.Ld2x0_c1f:
	v_max3_f32 v158, v82, v83, v84
	v_max3_f32 v158, v158, v85, v86
	v_max3_f32 v158, v158, v87, v88
	v_max3_f32 v158, v158, v89, v90
	v_max3_f32 v158, v158, v91, v92
	v_max3_f32 v158, v158, v93, v94
	v_max3_f32 v158, v158, v95, v96
	v_max_f32_e32 v158, v158, v97
	v_fmamk_f32 v158, v158, 0x3e38aa3b, v255
	v_cmp_gt_f32_e32 vcc, v158, v130
	s_cbranch_vccz .Ld2x0_f1a
	v_mov_b32_e32 v159, v158
	s_nop 1
	v_permlane32_swap_b32_e32 v159, v158
	v_max_f32_e32 v158, v158, v159
	v_cmp_gt_f32_e32 vcc, v158, v130
	s_nop 1
	v_cndmask_b32_e32 v159, v184, v158, vcc
	v_sub_f32_e32 v158, v184, v159
	v_exp_f32_e32 v158, v158
	v_mov_b32_e32 v184, v159
	v_mul_f32_e32 v0, v0, v158
	v_pk_mul_f32 v[64:65], v[64:65], v[158:159] op_sel_hi:[1,0]
	v_pk_mul_f32 v[62:63], v[62:63], v[158:159] op_sel_hi:[1,0]
	v_pk_mul_f32 v[60:61], v[60:61], v[158:159] op_sel_hi:[1,0]
	v_pk_mul_f32 v[58:59], v[58:59], v[158:159] op_sel_hi:[1,0]
	v_pk_mul_f32 v[56:57], v[56:57], v[158:159] op_sel_hi:[1,0]
	v_pk_mul_f32 v[54:55], v[54:55], v[158:159] op_sel_hi:[1,0]
	v_pk_mul_f32 v[52:53], v[52:53], v[158:159] op_sel_hi:[1,0]
	v_pk_mul_f32 v[50:51], v[50:51], v[158:159] op_sel_hi:[1,0]
	v_pk_mul_f32 v[48:49], v[48:49], v[158:159] op_sel_hi:[1,0]
	v_pk_mul_f32 v[46:47], v[46:47], v[158:159] op_sel_hi:[1,0]
	v_pk_mul_f32 v[44:45], v[44:45], v[158:159] op_sel_hi:[1,0]
	v_pk_mul_f32 v[42:43], v[42:43], v[158:159] op_sel_hi:[1,0]
	v_pk_mul_f32 v[40:41], v[40:41], v[158:159] op_sel_hi:[1,0]
	v_pk_mul_f32 v[38:39], v[38:39], v[158:159] op_sel_hi:[1,0]
	v_pk_mul_f32 v[36:37], v[36:37], v[158:159] op_sel_hi:[1,0]
	v_pk_mul_f32 v[34:35], v[34:35], v[158:159] op_sel_hi:[1,0]
	v_pk_mul_f32 v[32:33], v[32:33], v[158:159] op_sel_hi:[1,0]
	v_pk_mul_f32 v[30:31], v[30:31], v[158:159] op_sel_hi:[1,0]
	v_pk_mul_f32 v[28:29], v[28:29], v[158:159] op_sel_hi:[1,0]
	v_pk_mul_f32 v[26:27], v[26:27], v[158:159] op_sel_hi:[1,0]
	v_pk_mul_f32 v[24:25], v[24:25], v[158:159] op_sel_hi:[1,0]
	v_pk_mul_f32 v[22:23], v[22:23], v[158:159] op_sel_hi:[1,0]
	v_pk_mul_f32 v[20:21], v[20:21], v[158:159] op_sel_hi:[1,0]
	v_pk_mul_f32 v[18:19], v[18:19], v[158:159] op_sel_hi:[1,0]
	v_pk_mul_f32 v[16:17], v[16:17], v[158:159] op_sel_hi:[1,0]
	v_pk_mul_f32 v[14:15], v[14:15], v[158:159] op_sel_hi:[1,0]
	v_pk_mul_f32 v[12:13], v[12:13], v[158:159] op_sel_hi:[1,0]
	v_pk_mul_f32 v[10:11], v[10:11], v[158:159] op_sel_hi:[1,0]
	v_pk_mul_f32 v[8:9], v[8:9], v[158:159] op_sel_hi:[1,0]
	v_pk_mul_f32 v[6:7], v[6:7], v[158:159] op_sel_hi:[1,0]
	v_pk_mul_f32 v[4:5], v[4:5], v[158:159] op_sel_hi:[1,0]
	v_pk_mul_f32 v[2:3], v[2:3], v[158:159] op_sel_hi:[1,0]
.Ld2x0_f1a:
	v_sub_f32_e32 v186, v255, v184
	v_fmamk_f32 v82, v82, 0x3e38aa3b, v186
	v_exp_f32_e32 v82, v82
	v_fmamk_f32 v83, v83, 0x3e38aa3b, v186
	v_exp_f32_e32 v83, v83
	v_fmamk_f32 v84, v84, 0x3e38aa3b, v186
	v_exp_f32_e32 v84, v84
	v_fmamk_f32 v85, v85, 0x3e38aa3b, v186
	v_exp_f32_e32 v85, v85
	v_fmamk_f32 v86, v86, 0x3e38aa3b, v186
	v_exp_f32_e32 v86, v86
	v_fmamk_f32 v87, v87, 0x3e38aa3b, v186
	v_add_f32_e32 v156, v82, v83
	v_exp_f32_e32 v87, v87
	v_fmamk_f32 v88, v88, 0x3e38aa3b, v186
	v_add_f32_e32 v156, v84, v156
	v_exp_f32_e32 v88, v88
	v_fmamk_f32 v89, v89, 0x3e38aa3b, v186
	v_add_f32_e32 v156, v85, v156
	v_exp_f32_e32 v89, v89
	v_fmamk_f32 v90, v90, 0x3e38aa3b, v186
	v_add_f32_e32 v156, v86, v156
	v_exp_f32_e32 v90, v90
	v_fmamk_f32 v91, v91, 0x3e38aa3b, v186
	v_add_f32_e32 v156, v87, v156
	v_exp_f32_e32 v91, v91
	v_fmamk_f32 v92, v92, 0x3e38aa3b, v186
	v_add_f32_e32 v156, v88, v156
	v_exp_f32_e32 v92, v92
	v_fmamk_f32 v93, v93, 0x3e38aa3b, v186
	v_add_f32_e32 v156, v89, v156
	v_exp_f32_e32 v93, v93
	v_fmamk_f32 v94, v94, 0x3e38aa3b, v186
	v_add_f32_e32 v156, v90, v156
	v_exp_f32_e32 v94, v94
	v_fmamk_f32 v95, v95, 0x3e38aa3b, v186
	v_add_f32_e32 v156, v91, v156
	v_exp_f32_e32 v95, v95
	v_fmamk_f32 v96, v96, 0x3e38aa3b, v186
	v_add_f32_e32 v156, v92, v156
	v_exp_f32_e32 v96, v96
	v_fmamk_f32 v97, v97, 0x3e38aa3b, v186
	v_add_f32_e32 v156, v93, v156
	v_exp_f32_e32 v97, v97

; #define D2_X(t_) do { int i0_ = (t_) * 64 + rel0; i0_ = i0_ < -672 ? -672 : (i0_ > 640 ? 640 : i0_); d2_softmax(S0, c1, tab + (i0_ + 672), m_, l_, O, P0); \
;                       int i1_ = (t_) * 64 + 32 + rel0; i1_ = i1_ < -672 ? -672 : (i1_ > 640 ? 640 : i1_); d2_softmax(S1, c1, tab + (i1_ + 672), m_, l_, O, P1); } while (0)
; #define D2_Y(t_) do { if ((t_) + 1 < 32) { const LAS unsigned char* kb_ = kb0 + (((t_) + 1) & 1) * D2_KB; d2_qk(kb_, Q, S0); d2_qk(kb_ + 32 * 144, Q, S1); } \
;                       if ((t_) >= 0) { const LAS unsigned char* vb_ = vb_lane + ((t_) & 1) * D2_VB; d2_pv(vb_, P0, O); d2_pv(vb_ + 32 * 320, P1, O); } } while (0)
; __device__ __forceinline__ void diff2_item(const Params& p, LAS unsigned char* lds, const int item, const float lam, const float lam_init) {
;     ...
;         __syncthreads();
;         if (mp == 0) D2_Y(t); else D2_X(t);
.LBB0_341:
	s_or_b64 exec, exec, s[18:19]
	s_waitcnt lgkmcnt(0)
	s_barrier
	s_and_saveexec_b64 s[10:11], s[38:39]
	s_xor_b64 s[18:19], exec, s[10:11]
	s_cbranch_execz .LBB0_347
	s_setprio 3
	v_readfirstlane_b32 s98, v183
	s_mov_b32 s100, 0xfff9f990
	s_mov_b32 s101, -1
	s_add_i32 s99, s98, 32
	s_abs_i32 s98, s98
	s_abs_i32 s99, s99
	s_lshr_b32 s98, s98, 5
	s_lshr_b32 s99, s99, 5
	s_bitcmp1_b64 s[100:101], s99
	s_cbranch_scc1 .Ld2x1_i1f
	v_add_u32_e32 v156, 32, v183
	v_med3_i32 v156, v156, s16, v214
	v_lshl_add_u32 v156, v156, 2, s23
	v_add_u32_e32 v156, 0xa80, v156
	ds_read2_b32 v[186:187], v156 offset1:1
	ds_read2_b32 v[188:189], v156 offset0:2 offset1:3
	ds_read2_b32 v[190:191], v156 offset0:8 offset1:9
	ds_read2_b32 v[192:193], v156 offset0:10 offset1:11
	ds_read2_b32 v[194:195], v156 offset0:16 offset1:17
	ds_read2_b32 v[196:197], v156 offset0:18 offset1:19
	ds_read2_b32 v[198:199], v156 offset0:24 offset1:25
	ds_read2_b32 v[200:201], v156 offset0:26 offset1:27

; #define LAS __attribute__((address_space(3)))
; #define MFMA32(a, b, c) __builtin_amdgcn_mfma_f32_32x32x16_bf16((a), (b), (c), 0, 0, 0)
; #define TRR(p_) __builtin_amdgcn_ds_read_tr16_b64_v4i16((LAS v4s*)(p_))
; __device__ __forceinline__ void d2_pv(const LAS unsigned char* vb0, const v8s (&P)[2], v16f (&O)[4]) {
;     const LAS unsigned char* va = vb0; const LAS unsigned char* vc = vb0 + 16 * 320;
;     const v4s l0 = TRR(va), h0 = TRR(va + 2560), l1 = TRR(va + 64), h1 = TRR(va + 2624), l2 = TRR(va + 128), h2 = TRR(va + 2688), l3 = TRR(va + 192), h3 = TRR(va + 2752);
;     __builtin_amdgcn_sched_barrier(0);
;     const v4s m0 = TRR(vc), n0 = TRR(vc + 2560), m1 = TRR(vc + 64), n1 = TRR(vc + 2624), m2 = TRR(vc + 128), n2 = TRR(vc + 2688), m3 = TRR(vc + 192), n3 = TRR(vc + 2752);
;     O[0] = MFMA32(__builtin_shufflevector(l0, h0, 0, 1, 2, 3, 4, 5, 6, 7), P[0], O[0]);
;     O[1] = MFMA32(__builtin_shufflevector(l1, h1, 0, 1, 2, 3, 4, 5, 6, 7), P[0], O[1]);
;     O[2] = MFMA32(__builtin_shufflevector(l2, h2, 0, 1, 2, 3, 4, 5, 6, 7), P[0], O[2]);
;     O[3] = MFMA32(__builtin_shufflevector(l3, h3, 0, 1, 2, 3, 4, 5, 6, 7), P[0], O[3]);
;     __builtin_amdgcn_sched_barrier(0);
;     O[0] = MFMA32(__builtin_shufflevector(m0, n0, 0, 1, 2, 3, 4, 5, 6, 7), P[1], O[0]);
;     O[1] = MFMA32(__builtin_shufflevector(m1, n1, 0, 1, 2, 3, 4, 5, 6, 7), P[1], O[1]);
;     O[2] = MFMA32(__builtin_shufflevector(m2, n2, 0, 1, 2, 3, 4, 5, 6, 7), P[1], O[2]);
;     O[3] = MFMA32(__builtin_shufflevector(m3, n3, 0, 1, 2, 3, 4, 5, 6, 7), P[1], O[3]);
;     __builtin_amdgcn_sched_barrier(0);
; }
.LBB0_350:
	v_add_u32_e32 v0, s28, v180
	ds_read_b64_tr_b16 v[156:157], v0 offset:36864
	ds_read_b64_tr_b16 v[186:187], v0 offset:36928
	ds_read_b64_tr_b16 v[190:191], v0 offset:36992
	ds_read_b64_tr_b16 v[194:195], v0 offset:37056
	ds_read_b64_tr_b16 v[158:159], v0 offset:39424
	ds_read_b64_tr_b16 v[188:189], v0 offset:39488
	ds_read_b64_tr_b16 v[192:193], v0 offset:39552
	ds_read_b64_tr_b16 v[196:197], v0 offset:39616
	s_waitcnt lgkmcnt(3)
	v_mfma_f32_32x32x16_bf16 v[50:65], v[156:159], v[134:137], v[50:65]
	s_waitcnt lgkmcnt(2)
	v_mfma_f32_32x32x16_bf16 v[34:49], v[186:189], v[134:137], v[34:49]
	s_waitcnt lgkmcnt(1)
	v_mfma_f32_32x32x16_bf16 v[18:33], v[190:193], v[134:137], v[18:33]
	ds_read_b64_tr_b16 v[156:157], v0 offset:41984
	ds_read_b64_tr_b16 v[186:187], v0 offset:42048
	ds_read_b64_tr_b16 v[190:191], v0 offset:42112
	ds_read_b64_tr_b16 v[198:199], v0 offset:42176
	ds_read_b64_tr_b16 v[158:159], v0 offset:44544
	ds_read_b64_tr_b16 v[188:189], v0 offset:44608
	ds_read_b64_tr_b16 v[192:193], v0 offset:44672
	ds_read_b64_tr_b16 v[200:201], v0 offset:44736
	s_waitcnt lgkmcnt(8)
	v_mfma_f32_32x32x16_bf16 v[2:17], v[194:197], v[134:137], v[2:17]
	s_waitcnt lgkmcnt(3)
	v_mfma_f32_32x32x16_bf16 v[50:65], v[156:159], v[130:133], v[50:65]
	s_waitcnt lgkmcnt(2)
	v_mfma_f32_32x32x16_bf16 v[34:49], v[186:189], v[130:133], v[34:49]
	s_waitcnt lgkmcnt(1)
	v_mfma_f32_32x32x16_bf16 v[18:33], v[190:193], v[130:133], v[18:33]
	s_waitcnt lgkmcnt(0)
	v_mfma_f32_32x32x16_bf16 v[2:17], v[198:201], v[130:133], v[2:17]
	ds_read_b64_tr_b16 v[156:157], v0 offset:47104
	ds_read_b64_tr_b16 v[186:187], v0 offset:47168
	ds_read_b64_tr_b16 v[190:191], v0 offset:47232
	ds_read_b64_tr_b16 v[194:195], v0 offset:47296
	ds_read_b64_tr_b16 v[158:159], v0 offset:49664
	ds_read_b64_tr_b16 v[188:189], v0 offset:49728
	ds_read_b64_tr_b16 v[192:193], v0 offset:49792
	ds_read_b64_tr_b16 v[196:197], v0 offset:49856
	s_waitcnt lgkmcnt(3)
	v_mfma_f32_32x32x16_bf16 v[50:65], v[156:159], v[142:145], v[50:65]
	s_waitcnt lgkmcnt(2)
	v_mfma_f32_32x32x16_bf16 v[34:49], v[186:189], v[142:145], v[34:49]
	s_waitcnt lgkmcnt(1)
	v_mfma_f32_32x32x16_bf16 v[18:33], v[190:193], v[142:145], v[18:33]
	ds_read_b64_tr_b16 v[156:157], v0 offset:52224
	ds_read_b64_tr_b16 v[186:187], v0 offset:52288
	ds_read_b64_tr_b16 v[190:191], v0 offset:52352
	ds_read_b64_tr_b16 v[198:199], v0 offset:52416
	ds_read_b64_tr_b16 v[158:159], v0 offset:54784
	ds_read_b64_tr_b16 v[188:189], v0 offset:54848
	ds_read_b64_tr_b16 v[192:193], v0 offset:54912
	ds_read_b64_tr_b16 v[200:201], v0 offset:54976
	s_waitcnt lgkmcnt(8)
	v_mfma_f32_32x32x16_bf16 v[2:17], v[194:197], v[142:145], v[2:17]
	s_waitcnt lgkmcnt(3)
	v_mfma_f32_32x32x16_bf16 v[50:65], v[156:159], v[138:141], v[50:65]
	s_waitcnt lgkmcnt(2)
	v_mfma_f32_32x32x16_bf16 v[34:49], v[186:189], v[138:141], v[34:49]
	s_waitcnt lgkmcnt(1)
	v_mfma_f32_32x32x16_bf16 v[18:33], v[190:193], v[138:141], v[18:33]
	s_waitcnt lgkmcnt(0)
	v_mfma_f32_32x32x16_bf16 v[2:17], v[198:201], v[138:141], v[2:17]
	v_add_u32_e32 v252, 64, v183
	v_add_u32_e32 v253, 96, v183
	v_med3_i32 v252, v252, s16, v214
	v_med3_i32 v253, v253, s16, v214
	v_lshl_add_u32 v252, v252, 2, s23
	v_lshl_add_u32 v253, v253, 2, s23
	ds_read_b32 v254, v252 offset:2688
	ds_read_b32 v255, v253 offset:2688
